# grid barrier: XCD-last WG bumps the XCD generation word before its own buffer_inv (release others 1 inv earlier)
# speedup vs baseline: 1.0192x; 1.0192x over previous
.LBB0_1507:
	s_or_b64 exec, exec, s[2:3]
	s_mov_b64 s[2:3], exec
	v_mbcnt_lo_u32_b32 v0, s2, 0
	v_mbcnt_hi_u32_b32 v0, s3, v0
	v_cmp_eq_u32_e32 vcc, 0, v0
	s_waitcnt vmcnt(0)
	s_and_saveexec_b64 s[4:5], vcc
	s_cbranch_execnz .LBB0_1508
	buffer_inv sc1
	s_getpc_b64 s[98:99]

.LBB0_1508:
	s_bcnt1_i32_b64 s2, s[2:3]
	v_mov_b32_e32 v0, s2
	v_readlane_b32 s2, v253, 18
	v_readlane_b32 s3, v253, 19
	s_nop 4
	global_atomic_add v1, v0, s[2:3]
	buffer_inv sc1
	s_getpc_b64 s[98:99]
